# first PV group's first four V transpose-reads issued before the last QK MFMAs into free staging registers (on top of counted PV waits)
# speedup vs baseline: 1.0191x; 1.0029x over previous
; #define LAS __attribute__((address_space(3)))
; #define SBAR() __builtin_amdgcn_sched_barrier(0)
; __device__ __forceinline__ void qkt(f32x16& p0, f32x16& p1, const LAS char* Ks, const bf16x8* qr, const f32x16& negm, int r32, int hi) {
; #pragma unroll
;     for (int d0 = 0; d0 < 4; ++d0) { const int cb = (d0 * 16 + hi * 8) * 2;
;         const bf16x8 b0 = *(const LAS bf16x8*)(Ks + KSWZ(r32, cb));
;         const bf16x8 b1 = *(const LAS bf16x8*)(Ks + KSWZ(32 + r32, cb));
;         if (d0 == 0) { p0 = __builtin_amdgcn_mfma_f32_32x32x16_bf16(b0, qr[0], negm, 0, 0, 0); p1 = __builtin_amdgcn_mfma_f32_32x32x16_bf16(b1, qr[0], negm, 0, 0, 0); }
;         else { p0 = __builtin_amdgcn_mfma_f32_32x32x16_bf16(b0, qr[d0], p0, 0, 0, 0); p1 = __builtin_amdgcn_mfma_f32_32x32x16_bf16(b1, qr[d0], p1, 0, 0, 0); } }
; }
; __device__ __forceinline__ int v_st(int k, int c) { const int kk = (k & ~0xC) | ((k & 4) << 1) | ((k & 8) >> 1); return ((kk >> 3) * 4 + (c >> 5)) * 512 + ((kk & 7) * 32 + (c & 31)) * 2; }
; __device__ __forceinline__ int v_rd_base(int lane) { return ((lane & 3) << 3) | (((lane >> 2) & 3) << 6) | (((lane >> 4) & 1) << 5) | (((lane >> 5) & 1) << 8); }
; template <int OFF> __device__ __forceinline__ s16x4 tr_read(int vb) {
;     s16x4 r; asm volatile("ds_read_b64_tr_b16 %0, %1 offset:%2" : "=&v"(r) : "v"(vb), "i"(OFF) : "memory"); return r;
; }
; template <int D0> __device__ __forceinline__ void pv_one(f32x16& od, int vb, bf16x8 pa0, bf16x8 pa1, bf16x8 pa2, bf16x8 pa3) {
;     const s16x4 l0 = tr_read<v_rd_off(D0, 0, 0)>(vb), h0 = tr_read<v_rd_off(D0, 0, 1)>(vb), l1 = tr_read<v_rd_off(D0, 1, 0)>(vb), h1 = tr_read<v_rd_off(D0, 1, 1)>(vb);
;     const s16x4 l2 = tr_read<v_rd_off(D0, 2, 0)>(vb), h2 = tr_read<v_rd_off(D0, 2, 1)>(vb), l3 = tr_read<v_rd_off(D0, 3, 0)>(vb), h3 = tr_read<v_rd_off(D0, 3, 1)>(vb);
;     asm volatile("s_waitcnt lgkmcnt(0)" ::: "memory"); SBAR();
;     ...
;     od = __builtin_amdgcn_mfma_f32_32x32x16_bf16(pa0, PK(l0, h0), od, 0, 0, 0);
;     od = __builtin_amdgcn_mfma_f32_32x32x16_bf16(pa1, PK(l1, h1), od, 0, 0, 0);
;     od = __builtin_amdgcn_mfma_f32_32x32x16_bf16(pa2, PK(l2, h2), od, 0, 0, 0);
;     od = __builtin_amdgcn_mfma_f32_32x32x16_bf16(pa3, PK(l3, h3), od, 0, 0, 0);
;     ...
; }
; __device__ __forceinline__ void pv_d0(f32x16* o, int vb, bf16x8 pa0, bf16x8 pa1, bf16x8 pa2, bf16x8 pa3) {
.LBB0_591:
	s_add_i32 s2, s48, -4
	s_setprio 1
	s_and_b32 s61, s2, 3
	v_lshl_add_u32 v0, s61, 13, v241
	v_add_u32_e32 v6, v0, v237
	ds_read_b128 v[2:5], v6 offset:4096
	ds_read_b128 v[6:9], v6
	s_and_b32 s2, s39, 0xc000
	s_waitcnt lgkmcnt(1)
	v_mfma_f32_32x32x16_bf16 v[112:127], v[2:5], v[156:159], v[96:111]
	s_waitcnt lgkmcnt(0)
	v_mfma_f32_32x32x16_bf16 v[128:143], v[6:9], v[156:159], v[96:111]
	v_add_u32_e32 v6, v0, v238
	ds_read_b128 v[2:5], v6 offset:4096
	ds_read_b128 v[6:9], v6
	s_waitcnt lgkmcnt(1)
	v_mfma_f32_32x32x16_bf16 v[112:127], v[2:5], v[152:155], v[112:127]
	s_waitcnt lgkmcnt(0)
	v_mfma_f32_32x32x16_bf16 v[128:143], v[6:9], v[152:155], v[128:143]
	v_add_u32_e32 v6, v0, v239
	ds_read_b128 v[2:5], v6 offset:4096
	ds_read_b128 v[6:9], v6
	v_add_u32_e32 v0, v0, v240
	s_waitcnt lgkmcnt(1)
	v_mfma_f32_32x32x16_bf16 v[112:127], v[2:5], v[148:151], v[112:127]
	s_waitcnt lgkmcnt(0)
	v_mfma_f32_32x32x16_bf16 v[128:143], v[6:9], v[148:151], v[128:143]
	ds_read_b128 v[2:5], v0 offset:4096
	ds_read_b128 v[6:9], v0
	v_add_u32_e32 v0, s2, v242
	ds_read_b64_tr_b16 v[160:161], v0 offset:0
	ds_read_b64_tr_b16 v[162:163], v0 offset:0x800
	ds_read_b64_tr_b16 v[164:165], v0 offset:0x1000
	ds_read_b64_tr_b16 v[166:167], v0 offset:0x1800
	s_waitcnt lgkmcnt(5)
	v_mfma_f32_32x32x16_bf16 v[112:127], v[2:5], v[144:147], v[112:127]
	ds_read_b64_tr_b16 v[10:11], v0 offset:0x2000
	ds_read_b64_tr_b16 v[12:13], v0 offset:0x2800
	s_waitcnt lgkmcnt(6)
	v_mfma_f32_32x32x16_bf16 v[128:143], v[6:9], v[144:147], v[128:143]
	ds_read_b64_tr_b16 v[80:81], v0 offset:0x3000
	ds_read_b64_tr_b16 v[82:83], v0 offset:0x3800
	s_waitcnt lgkmcnt(6)
	v_mfma_f32_32x32x16_bf16 v[64:79], v[184:187], v[160:163], v[64:79]
	ds_read_b64_tr_b16 v[2:3], v0 offset:0x200
	ds_read_b64_tr_b16 v[4:5], v0 offset:0xa00
	s_waitcnt lgkmcnt(6)
	v_mfma_f32_32x32x16_bf16 v[64:79], v[188:191], v[164:167], v[64:79]
	ds_read_b64_tr_b16 v[6:7], v0 offset:0x1200
	ds_read_b64_tr_b16 v[8:9], v0 offset:0x1a00
	s_waitcnt lgkmcnt(6)
	v_mfma_f32_32x32x16_bf16 v[64:79], v[192:195], v[10:13], v[64:79]
	ds_read_b64_tr_b16 v[10:11], v0 offset:0x2200
	ds_read_b64_tr_b16 v[12:13], v0 offset:0x2a00
	s_waitcnt lgkmcnt(6)
	v_mfma_f32_32x32x16_bf16 v[64:79], v[196:199], v[80:83], v[64:79]
	ds_read_b64_tr_b16 v[80:81], v0 offset:0x3200
	ds_read_b64_tr_b16 v[82:83], v0 offset:0x3a00
	s_waitcnt lgkmcnt(6)
	v_mfma_f32_32x32x16_bf16 v[48:63], v[184:187], v[2:5], v[48:63]
	ds_read_b64_tr_b16 v[2:3], v0 offset:0x400
	ds_read_b64_tr_b16 v[4:5], v0 offset:0xc00
	s_waitcnt lgkmcnt(6)
	v_mfma_f32_32x32x16_bf16 v[48:63], v[188:191], v[6:9], v[48:63]
	ds_read_b64_tr_b16 v[6:7], v0 offset:0x1400
	ds_read_b64_tr_b16 v[8:9], v0 offset:0x1c00
	s_waitcnt lgkmcnt(6)
	v_mfma_f32_32x32x16_bf16 v[48:63], v[192:195], v[10:13], v[48:63]
	ds_read_b64_tr_b16 v[10:11], v0 offset:0x2400
	ds_read_b64_tr_b16 v[12:13], v0 offset:0x2c00
	s_waitcnt lgkmcnt(6)
	v_mfma_f32_32x32x16_bf16 v[48:63], v[196:199], v[80:83], v[48:63]
	ds_read_b64_tr_b16 v[80:81], v0 offset:0x3400
	ds_read_b64_tr_b16 v[82:83], v0 offset:0x3c00
	s_waitcnt lgkmcnt(6)
	v_mfma_f32_32x32x16_bf16 v[32:47], v[184:187], v[2:5], v[32:47]
	ds_read_b64_tr_b16 v[2:3], v0 offset:0x600
	ds_read_b64_tr_b16 v[4:5], v0 offset:0xe00
	s_waitcnt lgkmcnt(6)
	v_mfma_f32_32x32x16_bf16 v[32:47], v[188:191], v[6:9], v[32:47]
	ds_read_b64_tr_b16 v[6:7], v0 offset:0x1600
	ds_read_b64_tr_b16 v[8:9], v0 offset:0x1e00
	s_waitcnt lgkmcnt(6)
	v_mfma_f32_32x32x16_bf16 v[32:47], v[192:195], v[10:13], v[32:47]
	ds_read_b64_tr_b16 v[10:11], v0 offset:0x2600
	ds_read_b64_tr_b16 v[12:13], v0 offset:0x2e00
	s_waitcnt lgkmcnt(6)
	v_mfma_f32_32x32x16_bf16 v[32:47], v[196:199], v[80:83], v[32:47]
	ds_read_b64_tr_b16 v[80:81], v0 offset:0x3600
	ds_read_b64_tr_b16 v[82:83], v0 offset:0x3e00
	s_waitcnt lgkmcnt(6)
	v_mfma_f32_32x32x16_bf16 v[16:31], v[184:187], v[2:5], v[16:31]
	s_waitcnt lgkmcnt(4)
	v_mfma_f32_32x32x16_bf16 v[16:31], v[188:191], v[6:9], v[16:31]
	s_waitcnt lgkmcnt(2)
	v_mfma_f32_32x32x16_bf16 v[16:31], v[192:195], v[10:13], v[16:31]
	s_waitcnt lgkmcnt(0)
	v_mfma_f32_32x32x16_bf16 v[16:31], v[196:199], v[80:83], v[16:31]
	s_setprio 0
	s_add_i32 s2, s48, -2
	s_and_b32 s2, s2, 3
	s_lshl_b32 s3, s2, 14
	s_add_i32 s3, s3, 0
	s_waitcnt lgkmcnt(0)
	s_barrier
	v_add_u32_e32 v0, s3, v233
	s_add_i32 s49, s48, -1
	s_waitcnt vmcnt(2)
	ds_write_b128 v0, v[172:175]
	v_add_u32_e32 v0, s3, v234
	s_cmp_lt_u32 s49, s45
	s_waitcnt vmcnt(1)
	ds_write_b128 v0, v[176:179]
	v_lshl_add_u32 v0, s2, 13, v235
	s_cselect_b64 s[2:3], -1, 0
	s_cmp_ge_u32 s49, s45
	v_lshl_add_u64 v[188:189], v[218:219], 0, s[36:37]
	v_lshl_add_u64 v[14:15], v[216:217], 0, s[36:37]
	s_waitcnt vmcnt(0)
	ds_write_b128 v0, v[180:183]
	s_cbranch_scc1 .LBB0_593
	v_add_co_u32_e32 v2, vcc, 0xef40000, v188
	s_nop 1
	v_addc_co_u32_e32 v3, vcc, 0, v189, vcc
	v_add_co_u32_e32 v4, vcc, 0xef48000, v188
	s_nop 1
	v_addc_co_u32_e32 v5, vcc, 0, v189, vcc
	global_load_dwordx4 v[160:163], v[2:3], off
	global_load_dwordx4 v[164:167], v[4:5], off
	v_add_co_u32_e32 v2, vcc, 0xcf40000, v14
	s_nop 1
	v_addc_co_u32_e32 v3, vcc, 0, v15, vcc
	global_load_dwordx4 v[168:171], v[2:3], off

; __device__ __forceinline__ void partialSM(f32x16& p0, f32x16& p1, float& mhat, f32x16& negm, float& alpha, const bool first) {
;     ...
;     for (int r = 0; r < 16; ++r) p0[r] = __builtin_amdgcn_exp2f(p0[r]);
; }
; __device__ __forceinline__ void finishSM(f32x16& p0, f32x16& p1, float alpha, float& l_reg, bf16x8& pa0, bf16x8& pa1, bf16x8& pa2, bf16x8& pa3) {
; #pragma unroll
;     for (int r = 0; r < 16; ++r) p1[r] = __builtin_amdgcn_exp2f(p1[r]);
;     float ps = 0;
; #pragma unroll
;     for (int r = 0; r < 16; ++r) ps += p0[r];
; #pragma unroll
;     for (int r = 0; r < 16; ++r) ps += p1[r];
;     { auto rr = __builtin_amdgcn_permlane32_swap(__float_as_uint(ps), __float_as_uint(ps), false, false);
;       ps = __uint_as_float(rr[0]) + __uint_as_float(rr[1]); }
;     l_reg = l_reg * alpha + ps;
.LBB0_598:
	v_exp_f32_e32 v2, v128
	v_exp_f32_e32 v3, v129
	v_exp_f32_e32 v4, v130
	v_exp_f32_e32 v5, v131
	v_exp_f32_e32 v6, v132
	v_add_f32_e32 v132, 0, v2
	v_exp_f32_e32 v7, v133
	v_add_f32_e32 v132, v3, v132
	v_exp_f32_e32 v8, v134
	v_add_f32_e32 v132, v4, v132
	v_exp_f32_e32 v9, v135
	v_add_f32_e32 v132, v5, v132
	v_exp_f32_e32 v10, v136
	v_add_f32_e32 v132, v6, v132
	v_exp_f32_e32 v11, v137
	v_add_f32_e32 v132, v7, v132
	v_exp_f32_e32 v12, v138
	v_add_f32_e32 v132, v8, v132
	v_exp_f32_e32 v13, v139
	v_add_f32_e32 v132, v9, v132
	v_exp_f32_e32 v128, v140
	v_add_f32_e32 v132, v10, v132
	v_exp_f32_e32 v129, v141
	v_add_f32_e32 v132, v11, v132
	v_exp_f32_e32 v130, v142
	v_add_f32_e32 v132, v12, v132
	v_exp_f32_e32 v131, v143
	v_add_f32_e32 v132, v13, v132
	v_exp_f32_e32 v112, v112
	v_add_f32_e32 v132, v128, v132
	v_exp_f32_e32 v113, v113
	v_add_f32_e32 v132, v129, v132
	v_exp_f32_e32 v114, v114
	v_add_f32_e32 v132, v130, v132
	v_exp_f32_e32 v115, v115
	v_add_f32_e32 v132, v131, v132
	v_exp_f32_e32 v116, v116
	v_add_f32_e32 v132, v112, v132
	v_exp_f32_e32 v117, v117
	v_add_f32_e32 v132, v113, v132
	v_exp_f32_e32 v118, v118
	v_add_f32_e32 v132, v114, v132
	v_exp_f32_e32 v119, v119
	v_add_f32_e32 v132, v115, v132
	v_exp_f32_e32 v120, v120
	v_add_f32_e32 v132, v116, v132
	v_exp_f32_e32 v121, v121
	v_add_f32_e32 v132, v117, v132
	v_exp_f32_e32 v122, v122
	v_add_f32_e32 v132, v118, v132
	v_exp_f32_e32 v123, v123
	v_add_f32_e32 v132, v119, v132
	v_exp_f32_e32 v124, v124
	v_add_f32_e32 v132, v120, v132
	v_exp_f32_e32 v125, v125
	v_add_f32_e32 v132, v121, v132
	v_exp_f32_e32 v126, v126
	v_add_f32_e32 v132, v122, v132
	v_exp_f32_e32 v127, v127
	v_add_f32_e32 v132, v123, v132
	v_add_f32_e32 v132, v124, v132
	v_add_f32_e32 v132, v125, v132
	v_add_f32_e32 v132, v126, v132
	v_add_f32_e32 v190, v127, v132
	s_waitcnt lgkmcnt(0)
	s_barrier
; #define LAS __attribute__((address_space(3)))
; __device__ __forceinline__ void finishSM(f32x16& p0, f32x16& p1, float alpha, float& l_reg, bf16x8& pa0, bf16x8& pa1, bf16x8& pa2, bf16x8& pa3) {
; #pragma unroll
;     for (int r = 0; r < 16; ++r) p1[r] = __builtin_amdgcn_exp2f(p1[r]);
;     float ps = 0;
; #pragma unroll
;     for (int r = 0; r < 16; ++r) ps += p0[r];
; #pragma unroll
;     for (int r = 0; r < 16; ++r) ps += p1[r];
;     { auto rr = __builtin_amdgcn_permlane32_swap(__float_as_uint(ps), __float_as_uint(ps), false, false);
;       ps = __uint_as_float(rr[0]) + __uint_as_float(rr[1]); }
;     l_reg = l_reg * alpha + ps;
;     ...
;     PK4(p0, 0, pa0); PK4(p0, 8, pa1); PK4(p1, 0, pa2); PK4(p1, 8, pa3);
;     ...
; }
; __device__ __forceinline__ void qkt(f32x16& p0, f32x16& p1, const LAS char* Ks, const bf16x8* qr, const f32x16& negm, int r32, int hi) {
; #pragma unroll
;     for (int d0 = 0; d0 < 4; ++d0) { const int cb = (d0 * 16 + hi * 8) * 2;
;         const bf16x8 b0 = *(const LAS bf16x8*)(Ks + KSWZ(r32, cb));
;         const bf16x8 b1 = *(const LAS bf16x8*)(Ks + KSWZ(32 + r32, cb));
;         if (d0 == 0) { p0 = __builtin_amdgcn_mfma_f32_32x32x16_bf16(b0, qr[0], negm, 0, 0, 0); p1 = __builtin_amdgcn_mfma_f32_32x32x16_bf16(b1, qr[0], negm, 0, 0, 0); }
;         else { p0 = __builtin_amdgcn_mfma_f32_32x32x16_bf16(b0, qr[d0], p0, 0, 0, 0); p1 = __builtin_amdgcn_mfma_f32_32x32x16_bf16(b1, qr[d0], p1, 0, 0, 0); } }
; }
; __device__ __forceinline__ int v_st(int k, int c) { const int kk = (k & ~0xC) | ((k & 4) << 1) | ((k & 8) >> 1); return ((kk >> 3) * 4 + (c >> 5)) * 512 + ((kk & 7) * 32 + (c & 31)) * 2; }
; __device__ __forceinline__ int v_rd_base(int lane) { return ((lane & 3) << 3) | (((lane >> 2) & 3) << 6) | (((lane >> 4) & 1) << 5) | (((lane >> 5) & 1) << 8); }
; template <int OFF> __device__ __forceinline__ s16x4 tr_read(int vb) {
;     s16x4 r; asm volatile("ds_read_b64_tr_b16 %0, %1 offset:%2" : "=&v"(r) : "v"(vb), "i"(OFF) : "memory"); return r;
; }
; template <int D0> __device__ __forceinline__ void pv_one(f32x16& od, int vb, bf16x8 pa0, bf16x8 pa1, bf16x8 pa2, bf16x8 pa3) {
;     const s16x4 l0 = tr_read<v_rd_off(D0, 0, 0)>(vb), h0 = tr_read<v_rd_off(D0, 0, 1)>(vb), l1 = tr_read<v_rd_off(D0, 1, 0)>(vb), h1 = tr_read<v_rd_off(D0, 1, 1)>(vb);
	v_mov_b32_e32 v191, v190
	s_nop 1
	v_permlane32_swap_b32_e32 v190, v191
	v_cvt_pk_bf16_f32 v2, v2, v3
	v_cvt_pk_bf16_f32 v3, v4, v5
	v_cvt_pk_bf16_f32 v4, v6, v7
	v_cvt_pk_bf16_f32 v5, v8, v9
	v_cvt_pk_bf16_f32 v6, v10, v11
	v_cvt_pk_bf16_f32 v7, v12, v13
	v_cvt_pk_bf16_f32 v8, v128, v129
	v_cvt_pk_bf16_f32 v9, v130, v131
	v_cvt_pk_bf16_f32 v10, v112, v113
	v_cvt_pk_bf16_f32 v11, v114, v115
	v_cvt_pk_bf16_f32 v12, v116, v117
	v_cvt_pk_bf16_f32 v13, v118, v119
	v_cvt_pk_bf16_f32 v184, v120, v121
	v_cvt_pk_bf16_f32 v185, v122, v123
	v_cvt_pk_bf16_f32 v186, v124, v125
	v_cvt_pk_bf16_f32 v187, v126, v127
	v_permlane32_swap_b32_e32 v2, v4
	v_permlane32_swap_b32_e32 v3, v5
	v_permlane32_swap_b32_e32 v6, v8
	v_permlane32_swap_b32_e32 v7, v9
	v_permlane32_swap_b32_e32 v10, v12
	v_permlane32_swap_b32_e32 v11, v13
	v_permlane32_swap_b32_e32 v184, v186
	v_permlane32_swap_b32_e32 v185, v187
	s_setprio 1
	s_and_b32 s4, s38, 0x6000
	v_add_u32_e32 v200, s4, v241
	v_add_u32_e32 v112, v200, v237
	ds_read_b128 v[192:195], v112 offset:4096
	ds_read_b128 v[112:115], v112
	v_add_u32_e32 v196, v200, v238
	s_waitcnt lgkmcnt(0)
	v_mfma_f32_32x32x16_bf16 v[128:143], v[112:115], v[156:159], v[80:95]
	v_mfma_f32_32x32x16_bf16 v[112:127], v[192:195], v[156:159], v[80:95]
	ds_read_b128 v[192:195], v196 offset:4096
	ds_read_b128 v[196:199], v196
	s_waitcnt lgkmcnt(1)
	v_mfma_f32_32x32x16_bf16 v[112:127], v[192:195], v[152:155], v[112:127]
	s_waitcnt lgkmcnt(0)
	v_mfma_f32_32x32x16_bf16 v[128:143], v[196:199], v[152:155], v[128:143]
	v_add_u32_e32 v196, v200, v239
	ds_read_b128 v[192:195], v196 offset:4096
	ds_read_b128 v[196:199], v196
	s_waitcnt lgkmcnt(1)
	v_mfma_f32_32x32x16_bf16 v[112:127], v[192:195], v[148:151], v[112:127]
	s_waitcnt lgkmcnt(0)
	v_mfma_f32_32x32x16_bf16 v[128:143], v[196:199], v[148:151], v[128:143]
	v_add_u32_e32 v196, v200, v240
	ds_read_b128 v[192:195], v196 offset:4096
	ds_read_b128 v[196:199], v196
	v_lshl_add_u32 v200, s61, 14, v242
	ds_read_b64_tr_b16 v[172:173], v200 offset:0
	ds_read_b64_tr_b16 v[174:175], v200 offset:0x800
	ds_read_b64_tr_b16 v[176:177], v200 offset:0x1000
	ds_read_b64_tr_b16 v[178:179], v200 offset:0x1800
	s_waitcnt lgkmcnt(5)
	v_mfma_f32_32x32x16_bf16 v[112:127], v[192:195], v[144:147], v[112:127]
	ds_read_b64_tr_b16 v[220:221], v200 offset:0x2000
	ds_read_b64_tr_b16 v[222:223], v200 offset:0x2800
	s_waitcnt lgkmcnt(6)
	v_mfma_f32_32x32x16_bf16 v[128:143], v[196:199], v[144:147], v[128:143]
	ds_read_b64_tr_b16 v[244:245], v200 offset:0x3000
	ds_read_b64_tr_b16 v[246:247], v200 offset:0x3800
	s_waitcnt lgkmcnt(6)
	v_mfma_f32_32x32x16_bf16 v[64:79], v[2:5], v[172:175], v[64:79]
	ds_read_b64_tr_b16 v[192:193], v200 offset:0x200
	ds_read_b64_tr_b16 v[194:195], v200 offset:0xa00
	s_waitcnt lgkmcnt(6)
	v_mfma_f32_32x32x16_bf16 v[64:79], v[6:9], v[176:179], v[64:79]
	ds_read_b64_tr_b16 v[196:197], v200 offset:0x1200
	ds_read_b64_tr_b16 v[198:199], v200 offset:0x1a00
	s_waitcnt lgkmcnt(6)
	v_mfma_f32_32x32x16_bf16 v[64:79], v[10:13], v[220:223], v[64:79]
	ds_read_b64_tr_b16 v[220:221], v200 offset:0x2200
	ds_read_b64_tr_b16 v[222:223], v200 offset:0x2a00
	s_waitcnt lgkmcnt(6)
	v_mfma_f32_32x32x16_bf16 v[64:79], v[184:187], v[244:247], v[64:79]
	ds_read_b64_tr_b16 v[244:245], v200 offset:0x3200
	ds_read_b64_tr_b16 v[246:247], v200 offset:0x3a00
	s_waitcnt lgkmcnt(6)
	v_mfma_f32_32x32x16_bf16 v[48:63], v[2:5], v[192:195], v[48:63]
	ds_read_b64_tr_b16 v[192:193], v200 offset:0x400
	ds_read_b64_tr_b16 v[194:195], v200 offset:0xc00
	s_waitcnt lgkmcnt(6)
	v_mfma_f32_32x32x16_bf16 v[48:63], v[6:9], v[196:199], v[48:63]
	ds_read_b64_tr_b16 v[196:197], v200 offset:0x1400
	ds_read_b64_tr_b16 v[198:199], v200 offset:0x1c00
	s_waitcnt lgkmcnt(6)
	v_mfma_f32_32x32x16_bf16 v[48:63], v[10:13], v[220:223], v[48:63]
	ds_read_b64_tr_b16 v[220:221], v200 offset:0x2400
	ds_read_b64_tr_b16 v[222:223], v200 offset:0x2c00
	s_waitcnt lgkmcnt(6)
	v_mfma_f32_32x32x16_bf16 v[48:63], v[184:187], v[244:247], v[48:63]
	ds_read_b64_tr_b16 v[244:245], v200 offset:0x3400
	ds_read_b64_tr_b16 v[246:247], v200 offset:0x3c00
	s_waitcnt lgkmcnt(6)
	v_mfma_f32_32x32x16_bf16 v[32:47], v[2:5], v[192:195], v[32:47]
	ds_read_b64_tr_b16 v[192:193], v200 offset:0x600
	ds_read_b64_tr_b16 v[194:195], v200 offset:0xe00
	s_waitcnt lgkmcnt(6)
	v_mfma_f32_32x32x16_bf16 v[32:47], v[6:9], v[196:199], v[32:47]
	ds_read_b64_tr_b16 v[196:197], v200 offset:0x1600
	ds_read_b64_tr_b16 v[198:199], v200 offset:0x1e00
	s_waitcnt lgkmcnt(6)
	v_mfma_f32_32x32x16_bf16 v[32:47], v[10:13], v[220:223], v[32:47]
	ds_read_b64_tr_b16 v[220:221], v200 offset:0x2600
	ds_read_b64_tr_b16 v[222:223], v200 offset:0x2e00
	s_waitcnt lgkmcnt(6)
	v_mfma_f32_32x32x16_bf16 v[32:47], v[184:187], v[244:247], v[32:47]
	ds_read_b64_tr_b16 v[244:245], v200 offset:0x3600
	ds_read_b64_tr_b16 v[246:247], v200 offset:0x3e00
	s_waitcnt lgkmcnt(6)
	v_mfma_f32_32x32x16_bf16 v[16:31], v[2:5], v[192:195], v[16:31]
	s_waitcnt lgkmcnt(4)
	v_mfma_f32_32x32x16_bf16 v[16:31], v[6:9], v[196:199], v[16:31]
	s_waitcnt lgkmcnt(2)
	v_mfma_f32_32x32x16_bf16 v[16:31], v[10:13], v[220:223], v[16:31]
	s_waitcnt lgkmcnt(0)
	v_mfma_f32_32x32x16_bf16 v[16:31], v[184:187], v[244:247], v[16:31]
	s_setprio 0
	s_waitcnt lgkmcnt(0)
	s_barrier
	s_andn2_b64 vcc, exec, s[2:3]
	s_cbranch_vccnz .LBB0_600
	s_and_b32 s2, s49, 3
	s_lshl_b32 s3, s2, 14
	s_add_i32 s3, s3, 0
	v_add_u32_e32 v2, s3, v233
	v_add_u32_e32 v3, s3, v234
	v_lshl_add_u32 v4, s2, 13, v235
	s_waitcnt vmcnt(2)
	ds_write_b128 v2, v[160:163]
	s_waitcnt vmcnt(1)
	ds_write_b128 v3, v[164:167]
	s_waitcnt vmcnt(0)
	ds_write_b128 v4, v[168:171]

; #define LAS __attribute__((address_space(3)))
; #define SBAR() __builtin_amdgcn_sched_barrier(0)
; __device__ __forceinline__ void qkt(f32x16& p0, f32x16& p1, const LAS char* Ks, const bf16x8* qr, const f32x16& negm, int r32, int hi) {
; #pragma unroll
;     for (int d0 = 0; d0 < 4; ++d0) { const int cb = (d0 * 16 + hi * 8) * 2;
;         const bf16x8 b0 = *(const LAS bf16x8*)(Ks + KSWZ(r32, cb));
;         const bf16x8 b1 = *(const LAS bf16x8*)(Ks + KSWZ(32 + r32, cb));
;         if (d0 == 0) { p0 = __builtin_amdgcn_mfma_f32_32x32x16_bf16(b0, qr[0], negm, 0, 0, 0); p1 = __builtin_amdgcn_mfma_f32_32x32x16_bf16(b1, qr[0], negm, 0, 0, 0); }
;         else { p0 = __builtin_amdgcn_mfma_f32_32x32x16_bf16(b0, qr[d0], p0, 0, 0, 0); p1 = __builtin_amdgcn_mfma_f32_32x32x16_bf16(b1, qr[d0], p1, 0, 0, 0); } }
; }
; __device__ __forceinline__ int v_st(int k, int c) { const int kk = (k & ~0xC) | ((k & 4) << 1) | ((k & 8) >> 1); return ((kk >> 3) * 4 + (c >> 5)) * 512 + ((kk & 7) * 32 + (c & 31)) * 2; }
; __device__ __forceinline__ int v_rd_base(int lane) { return ((lane & 3) << 3) | (((lane >> 2) & 3) << 6) | (((lane >> 4) & 1) << 5) | (((lane >> 5) & 1) << 8); }
; template <int OFF> __device__ __forceinline__ s16x4 tr_read(int vb) {
;     s16x4 r; asm volatile("ds_read_b64_tr_b16 %0, %1 offset:%2" : "=&v"(r) : "v"(vb), "i"(OFF) : "memory"); return r;
; }
; template <int D0> __device__ __forceinline__ void pv_one(f32x16& od, int vb, bf16x8 pa0, bf16x8 pa1, bf16x8 pa2, bf16x8 pa3) {
;     const s16x4 l0 = tr_read<v_rd_off(D0, 0, 0)>(vb), h0 = tr_read<v_rd_off(D0, 0, 1)>(vb), l1 = tr_read<v_rd_off(D0, 1, 0)>(vb), h1 = tr_read<v_rd_off(D0, 1, 1)>(vb);
;     const s16x4 l2 = tr_read<v_rd_off(D0, 2, 0)>(vb), h2 = tr_read<v_rd_off(D0, 2, 1)>(vb), l3 = tr_read<v_rd_off(D0, 3, 0)>(vb), h3 = tr_read<v_rd_off(D0, 3, 1)>(vb);
;     asm volatile("s_waitcnt lgkmcnt(0)" ::: "memory"); SBAR();
;     ...
;     od = __builtin_amdgcn_mfma_f32_32x32x16_bf16(pa0, PK(l0, h0), od, 0, 0, 0);
;     od = __builtin_amdgcn_mfma_f32_32x32x16_bf16(pa1, PK(l1, h1), od, 0, 0, 0);
;     od = __builtin_amdgcn_mfma_f32_32x32x16_bf16(pa2, PK(l2, h2), od, 0, 0, 0);
;     od = __builtin_amdgcn_mfma_f32_32x32x16_bf16(pa3, PK(l3, h3), od, 0, 0, 0);
;     ...
; }
; __device__ __forceinline__ void pv_d0(f32x16* o, int vb, bf16x8 pa0, bf16x8 pa1, bf16x8 pa2, bf16x8 pa3) {
.LBB0_622:
	s_add_i32 s2, s34, -4
	s_setprio 1
	s_and_b32 s38, s2, 3
	v_lshl_add_u32 v0, s38, 13, v241
	v_add_u32_e32 v6, v0, v240
	ds_read_b128 v[2:5], v6 offset:4096
	ds_read_b128 v[6:9], v6
	s_and_b32 s2, s19, 0xc000
	s_waitcnt lgkmcnt(1)
	v_mfma_f32_32x32x16_bf16 v[112:127], v[2:5], v[156:159], v[96:111]
	s_waitcnt lgkmcnt(0)
	v_mfma_f32_32x32x16_bf16 v[128:143], v[6:9], v[156:159], v[96:111]
	v_add_u32_e32 v6, v0, v239
	ds_read_b128 v[2:5], v6 offset:4096
	ds_read_b128 v[6:9], v6
	s_waitcnt lgkmcnt(1)
	v_mfma_f32_32x32x16_bf16 v[112:127], v[2:5], v[152:155], v[112:127]
	s_waitcnt lgkmcnt(0)
	v_mfma_f32_32x32x16_bf16 v[128:143], v[6:9], v[152:155], v[128:143]
	v_add_u32_e32 v6, v0, v236
	ds_read_b128 v[2:5], v6 offset:4096
	ds_read_b128 v[6:9], v6
	v_add_u32_e32 v0, v0, v237
	s_waitcnt lgkmcnt(1)
	v_mfma_f32_32x32x16_bf16 v[112:127], v[2:5], v[148:151], v[112:127]
	s_waitcnt lgkmcnt(0)
	v_mfma_f32_32x32x16_bf16 v[128:143], v[6:9], v[148:151], v[128:143]
	ds_read_b128 v[2:5], v0 offset:4096
	ds_read_b128 v[6:9], v0
	v_add_u32_e32 v0, s2, v242
	ds_read_b64_tr_b16 v[160:161], v0 offset:0
	ds_read_b64_tr_b16 v[162:163], v0 offset:0x800
	ds_read_b64_tr_b16 v[164:165], v0 offset:0x1000
	ds_read_b64_tr_b16 v[166:167], v0 offset:0x1800
	s_waitcnt lgkmcnt(5)
	v_mfma_f32_32x32x16_bf16 v[112:127], v[2:5], v[144:147], v[112:127]
	ds_read_b64_tr_b16 v[10:11], v0 offset:0x2000
	ds_read_b64_tr_b16 v[12:13], v0 offset:0x2800
	s_waitcnt lgkmcnt(6)
	v_mfma_f32_32x32x16_bf16 v[128:143], v[6:9], v[144:147], v[128:143]
	ds_read_b64_tr_b16 v[80:81], v0 offset:0x3000
	ds_read_b64_tr_b16 v[82:83], v0 offset:0x3800
	s_waitcnt lgkmcnt(6)
	v_mfma_f32_32x32x16_bf16 v[64:79], v[184:187], v[160:163], v[64:79]
	ds_read_b64_tr_b16 v[2:3], v0 offset:0x200
	ds_read_b64_tr_b16 v[4:5], v0 offset:0xa00
	s_waitcnt lgkmcnt(6)
	v_mfma_f32_32x32x16_bf16 v[64:79], v[188:191], v[164:167], v[64:79]
	ds_read_b64_tr_b16 v[6:7], v0 offset:0x1200
	ds_read_b64_tr_b16 v[8:9], v0 offset:0x1a00
	s_waitcnt lgkmcnt(6)
	v_mfma_f32_32x32x16_bf16 v[64:79], v[192:195], v[10:13], v[64:79]
	ds_read_b64_tr_b16 v[10:11], v0 offset:0x2200
	ds_read_b64_tr_b16 v[12:13], v0 offset:0x2a00
	s_waitcnt lgkmcnt(6)
	v_mfma_f32_32x32x16_bf16 v[64:79], v[196:199], v[80:83], v[64:79]
	ds_read_b64_tr_b16 v[80:81], v0 offset:0x3200
	ds_read_b64_tr_b16 v[82:83], v0 offset:0x3a00
	s_waitcnt lgkmcnt(6)
	v_mfma_f32_32x32x16_bf16 v[48:63], v[184:187], v[2:5], v[48:63]
	ds_read_b64_tr_b16 v[2:3], v0 offset:0x400
	ds_read_b64_tr_b16 v[4:5], v0 offset:0xc00
	s_waitcnt lgkmcnt(6)
	v_mfma_f32_32x32x16_bf16 v[48:63], v[188:191], v[6:9], v[48:63]
	ds_read_b64_tr_b16 v[6:7], v0 offset:0x1400
	ds_read_b64_tr_b16 v[8:9], v0 offset:0x1c00
	s_waitcnt lgkmcnt(6)
	v_mfma_f32_32x32x16_bf16 v[48:63], v[192:195], v[10:13], v[48:63]
	ds_read_b64_tr_b16 v[10:11], v0 offset:0x2400
	ds_read_b64_tr_b16 v[12:13], v0 offset:0x2c00
	s_waitcnt lgkmcnt(6)
	v_mfma_f32_32x32x16_bf16 v[48:63], v[196:199], v[80:83], v[48:63]
	ds_read_b64_tr_b16 v[80:81], v0 offset:0x3400
	ds_read_b64_tr_b16 v[82:83], v0 offset:0x3c00
	s_waitcnt lgkmcnt(6)
	v_mfma_f32_32x32x16_bf16 v[32:47], v[184:187], v[2:5], v[32:47]
	ds_read_b64_tr_b16 v[2:3], v0 offset:0x600
	ds_read_b64_tr_b16 v[4:5], v0 offset:0xe00
	s_waitcnt lgkmcnt(6)
	v_mfma_f32_32x32x16_bf16 v[32:47], v[188:191], v[6:9], v[32:47]
	ds_read_b64_tr_b16 v[6:7], v0 offset:0x1600
	ds_read_b64_tr_b16 v[8:9], v0 offset:0x1e00
	s_waitcnt lgkmcnt(6)
	v_mfma_f32_32x32x16_bf16 v[32:47], v[192:195], v[10:13], v[32:47]
	ds_read_b64_tr_b16 v[10:11], v0 offset:0x2600
	ds_read_b64_tr_b16 v[12:13], v0 offset:0x2e00
	s_waitcnt lgkmcnt(6)
	v_mfma_f32_32x32x16_bf16 v[32:47], v[196:199], v[80:83], v[32:47]
	ds_read_b64_tr_b16 v[80:81], v0 offset:0x3600
	ds_read_b64_tr_b16 v[82:83], v0 offset:0x3e00
	s_waitcnt lgkmcnt(6)
	v_mfma_f32_32x32x16_bf16 v[16:31], v[184:187], v[2:5], v[16:31]
	s_waitcnt lgkmcnt(4)
	v_mfma_f32_32x32x16_bf16 v[16:31], v[188:191], v[6:9], v[16:31]
	s_waitcnt lgkmcnt(2)
	v_mfma_f32_32x32x16_bf16 v[16:31], v[192:195], v[10:13], v[16:31]
	s_waitcnt lgkmcnt(0)
	v_mfma_f32_32x32x16_bf16 v[16:31], v[196:199], v[80:83], v[16:31]
	s_setprio 0
	s_add_i32 s2, s34, -2
	s_and_b32 s2, s2, 3
	s_lshl_b32 s3, s2, 14
	s_add_i32 s3, s3, 0
	s_waitcnt lgkmcnt(0)
	s_barrier
	v_add_u32_e32 v0, s3, v233
	s_add_i32 s35, s34, -1
	s_waitcnt vmcnt(2)
	ds_write_b128 v0, v[172:175]
	v_add_u32_e32 v0, s3, v234
	s_cmp_lt_u32 s35, s45
	s_waitcnt vmcnt(1)
	ds_write_b128 v0, v[176:179]
	v_lshl_add_u32 v0, s2, 13, v235
	s_cselect_b64 s[2:3], -1, 0
	s_cmp_ge_u32 s35, s45
	v_lshl_add_u64 v[188:189], v[218:219], 0, s[36:37]
	v_lshl_add_u64 v[14:15], v[216:217], 0, s[36:37]
	s_waitcnt vmcnt(0)
	ds_write_b128 v0, v[180:183]
	s_cbranch_scc1 .LBB0_624
	v_add_co_u32_e32 v2, vcc, 0xef40000, v188
	s_nop 1
	v_addc_co_u32_e32 v3, vcc, 0, v189, vcc
	v_add_co_u32_e32 v4, vcc, 0xef48000, v188
	s_nop 1
	v_addc_co_u32_e32 v5, vcc, 0, v189, vcc
	global_load_dwordx4 v[160:163], v[2:3], off
	global_load_dwordx4 v[164:167], v[4:5], off
	v_add_co_u32_e32 v2, vcc, 0xcf40000, v14
	s_nop 1
	v_addc_co_u32_e32 v3, vcc, 0, v15, vcc
	global_load_dwordx4 v[168:171], v[2:3], off offset:128

; __device__ __forceinline__ void partialSM(f32x16& p0, f32x16& p1, float& mhat, f32x16& negm, float& alpha, const bool first) {
;     ...
;     for (int r = 0; r < 16; ++r) p0[r] = __builtin_amdgcn_exp2f(p0[r]);
; }
; __device__ __forceinline__ void finishSM(f32x16& p0, f32x16& p1, float alpha, float& l_reg, bf16x8& pa0, bf16x8& pa1, bf16x8& pa2, bf16x8& pa3) {
; #pragma unroll
;     for (int r = 0; r < 16; ++r) p1[r] = __builtin_amdgcn_exp2f(p1[r]);
;     float ps = 0;
; #pragma unroll
;     for (int r = 0; r < 16; ++r) ps += p0[r];
; #pragma unroll
;     for (int r = 0; r < 16; ++r) ps += p1[r];
;     { auto rr = __builtin_amdgcn_permlane32_swap(__float_as_uint(ps), __float_as_uint(ps), false, false);
;       ps = __uint_as_float(rr[0]) + __uint_as_float(rr[1]); }
;     l_reg = l_reg * alpha + ps;
.LBB0_629:
	v_exp_f32_e32 v2, v128
	v_exp_f32_e32 v3, v129
	v_exp_f32_e32 v4, v130
	v_exp_f32_e32 v5, v131
	v_exp_f32_e32 v6, v132
	v_add_f32_e32 v132, 0, v2
	v_exp_f32_e32 v7, v133
	v_add_f32_e32 v132, v3, v132
	v_exp_f32_e32 v8, v134
	v_add_f32_e32 v132, v4, v132
	v_exp_f32_e32 v9, v135
	v_add_f32_e32 v132, v5, v132
	v_exp_f32_e32 v10, v136
	v_add_f32_e32 v132, v6, v132
	v_exp_f32_e32 v11, v137
	v_add_f32_e32 v132, v7, v132
	v_exp_f32_e32 v12, v138
	v_add_f32_e32 v132, v8, v132
	v_exp_f32_e32 v13, v139
	v_add_f32_e32 v132, v9, v132
	v_exp_f32_e32 v128, v140
	v_add_f32_e32 v132, v10, v132
	v_exp_f32_e32 v129, v141
	v_add_f32_e32 v132, v11, v132
	v_exp_f32_e32 v130, v142
	v_add_f32_e32 v132, v12, v132
	v_exp_f32_e32 v131, v143
	v_add_f32_e32 v132, v13, v132
	v_exp_f32_e32 v112, v112
	v_add_f32_e32 v132, v128, v132
	v_exp_f32_e32 v113, v113
	v_add_f32_e32 v132, v129, v132
	v_exp_f32_e32 v114, v114
	v_add_f32_e32 v132, v130, v132
	v_exp_f32_e32 v115, v115
	v_add_f32_e32 v132, v131, v132
	v_exp_f32_e32 v116, v116
	v_add_f32_e32 v132, v112, v132
	v_exp_f32_e32 v117, v117
	v_add_f32_e32 v132, v113, v132
	v_exp_f32_e32 v118, v118
	v_add_f32_e32 v132, v114, v132
	v_exp_f32_e32 v119, v119
	v_add_f32_e32 v132, v115, v132
	v_exp_f32_e32 v120, v120
	v_add_f32_e32 v132, v116, v132
	v_exp_f32_e32 v121, v121
	v_add_f32_e32 v132, v117, v132
	v_exp_f32_e32 v122, v122
	v_add_f32_e32 v132, v118, v132
	v_exp_f32_e32 v123, v123
	v_add_f32_e32 v132, v119, v132
	v_exp_f32_e32 v124, v124
	v_add_f32_e32 v132, v120, v132
	v_exp_f32_e32 v125, v125
	v_add_f32_e32 v132, v121, v132
	v_exp_f32_e32 v126, v126
	v_add_f32_e32 v132, v122, v132
	v_exp_f32_e32 v127, v127
	v_add_f32_e32 v132, v123, v132
	v_add_f32_e32 v132, v124, v132
	v_add_f32_e32 v132, v125, v132
	v_add_f32_e32 v132, v126, v132
	v_add_f32_e32 v190, v127, v132
	s_waitcnt lgkmcnt(0)
	s_barrier
; #define LAS __attribute__((address_space(3)))
; __device__ __forceinline__ void finishSM(f32x16& p0, f32x16& p1, float alpha, float& l_reg, bf16x8& pa0, bf16x8& pa1, bf16x8& pa2, bf16x8& pa3) {
; #pragma unroll
;     for (int r = 0; r < 16; ++r) p1[r] = __builtin_amdgcn_exp2f(p1[r]);
;     float ps = 0;
; #pragma unroll
;     for (int r = 0; r < 16; ++r) ps += p0[r];
; #pragma unroll
;     for (int r = 0; r < 16; ++r) ps += p1[r];
;     { auto rr = __builtin_amdgcn_permlane32_swap(__float_as_uint(ps), __float_as_uint(ps), false, false);
;       ps = __uint_as_float(rr[0]) + __uint_as_float(rr[1]); }
;     l_reg = l_reg * alpha + ps;
;     ...
;     PK4(p0, 0, pa0); PK4(p0, 8, pa1); PK4(p1, 0, pa2); PK4(p1, 8, pa3);
;     ...
; }
; __device__ __forceinline__ void qkt(f32x16& p0, f32x16& p1, const LAS char* Ks, const bf16x8* qr, const f32x16& negm, int r32, int hi) {
; #pragma unroll
;     for (int d0 = 0; d0 < 4; ++d0) { const int cb = (d0 * 16 + hi * 8) * 2;
;         const bf16x8 b0 = *(const LAS bf16x8*)(Ks + KSWZ(r32, cb));
;         const bf16x8 b1 = *(const LAS bf16x8*)(Ks + KSWZ(32 + r32, cb));
;         if (d0 == 0) { p0 = __builtin_amdgcn_mfma_f32_32x32x16_bf16(b0, qr[0], negm, 0, 0, 0); p1 = __builtin_amdgcn_mfma_f32_32x32x16_bf16(b1, qr[0], negm, 0, 0, 0); }
;         else { p0 = __builtin_amdgcn_mfma_f32_32x32x16_bf16(b0, qr[d0], p0, 0, 0, 0); p1 = __builtin_amdgcn_mfma_f32_32x32x16_bf16(b1, qr[d0], p1, 0, 0, 0); } }
; }
; __device__ __forceinline__ int v_st(int k, int c) { const int kk = (k & ~0xC) | ((k & 4) << 1) | ((k & 8) >> 1); return ((kk >> 3) * 4 + (c >> 5)) * 512 + ((kk & 7) * 32 + (c & 31)) * 2; }
; __device__ __forceinline__ int v_rd_base(int lane) { return ((lane & 3) << 3) | (((lane >> 2) & 3) << 6) | (((lane >> 4) & 1) << 5) | (((lane >> 5) & 1) << 8); }
; template <int OFF> __device__ __forceinline__ s16x4 tr_read(int vb) {
;     s16x4 r; asm volatile("ds_read_b64_tr_b16 %0, %1 offset:%2" : "=&v"(r) : "v"(vb), "i"(OFF) : "memory"); return r;
; }
; template <int D0> __device__ __forceinline__ void pv_one(f32x16& od, int vb, bf16x8 pa0, bf16x8 pa1, bf16x8 pa2, bf16x8 pa3) {
;     const s16x4 l0 = tr_read<v_rd_off(D0, 0, 0)>(vb), h0 = tr_read<v_rd_off(D0, 0, 1)>(vb), l1 = tr_read<v_rd_off(D0, 1, 0)>(vb), h1 = tr_read<v_rd_off(D0, 1, 1)>(vb);
	v_mov_b32_e32 v191, v190
	s_nop 1
	v_permlane32_swap_b32_e32 v190, v191
	v_cvt_pk_bf16_f32 v2, v2, v3
	v_cvt_pk_bf16_f32 v3, v4, v5
	v_cvt_pk_bf16_f32 v4, v6, v7
	v_cvt_pk_bf16_f32 v5, v8, v9
	v_cvt_pk_bf16_f32 v6, v10, v11
	v_cvt_pk_bf16_f32 v7, v12, v13
	v_cvt_pk_bf16_f32 v8, v128, v129
	v_cvt_pk_bf16_f32 v9, v130, v131
	v_cvt_pk_bf16_f32 v10, v112, v113
	v_cvt_pk_bf16_f32 v11, v114, v115
	v_cvt_pk_bf16_f32 v12, v116, v117
	v_cvt_pk_bf16_f32 v13, v118, v119
	v_cvt_pk_bf16_f32 v184, v120, v121
	v_cvt_pk_bf16_f32 v185, v122, v123
	v_cvt_pk_bf16_f32 v186, v124, v125
	v_cvt_pk_bf16_f32 v187, v126, v127
	v_permlane32_swap_b32_e32 v2, v4
	v_permlane32_swap_b32_e32 v3, v5
	v_permlane32_swap_b32_e32 v6, v8
	v_permlane32_swap_b32_e32 v7, v9
	v_permlane32_swap_b32_e32 v10, v12
	v_permlane32_swap_b32_e32 v11, v13
	v_permlane32_swap_b32_e32 v184, v186
	v_permlane32_swap_b32_e32 v185, v187
	s_setprio 1
	s_and_b32 s4, s18, 0x6000
	v_add_u32_e32 v200, s4, v241
	v_add_u32_e32 v112, v200, v240
	ds_read_b128 v[192:195], v112 offset:4096
	ds_read_b128 v[112:115], v112
	v_add_u32_e32 v196, v200, v239
	s_waitcnt lgkmcnt(0)
	v_mfma_f32_32x32x16_bf16 v[128:143], v[112:115], v[156:159], v[80:95]
	v_mfma_f32_32x32x16_bf16 v[112:127], v[192:195], v[156:159], v[80:95]
	ds_read_b128 v[192:195], v196 offset:4096
	ds_read_b128 v[196:199], v196
	s_waitcnt lgkmcnt(1)
	v_mfma_f32_32x32x16_bf16 v[112:127], v[192:195], v[152:155], v[112:127]
	s_waitcnt lgkmcnt(0)
	v_mfma_f32_32x32x16_bf16 v[128:143], v[196:199], v[152:155], v[128:143]
	v_add_u32_e32 v196, v200, v236
	ds_read_b128 v[192:195], v196 offset:4096
	ds_read_b128 v[196:199], v196
	s_waitcnt lgkmcnt(1)
	v_mfma_f32_32x32x16_bf16 v[112:127], v[192:195], v[148:151], v[112:127]
	s_waitcnt lgkmcnt(0)
	v_mfma_f32_32x32x16_bf16 v[128:143], v[196:199], v[148:151], v[128:143]
	v_add_u32_e32 v196, v200, v237
	ds_read_b128 v[192:195], v196 offset:4096
	ds_read_b128 v[196:199], v196
	v_lshl_add_u32 v200, s38, 14, v242
	ds_read_b64_tr_b16 v[172:173], v200 offset:0
	ds_read_b64_tr_b16 v[174:175], v200 offset:0x800
	ds_read_b64_tr_b16 v[176:177], v200 offset:0x1000
	ds_read_b64_tr_b16 v[178:179], v200 offset:0x1800
	s_waitcnt lgkmcnt(5)
	v_mfma_f32_32x32x16_bf16 v[112:127], v[192:195], v[144:147], v[112:127]
	ds_read_b64_tr_b16 v[220:221], v200 offset:0x2000
	ds_read_b64_tr_b16 v[222:223], v200 offset:0x2800
	s_waitcnt lgkmcnt(6)
	v_mfma_f32_32x32x16_bf16 v[128:143], v[196:199], v[144:147], v[128:143]
	ds_read_b64_tr_b16 v[244:245], v200 offset:0x3000
	ds_read_b64_tr_b16 v[246:247], v200 offset:0x3800
	s_waitcnt lgkmcnt(6)
	v_mfma_f32_32x32x16_bf16 v[64:79], v[2:5], v[172:175], v[64:79]
	ds_read_b64_tr_b16 v[192:193], v200 offset:0x200
	ds_read_b64_tr_b16 v[194:195], v200 offset:0xa00
	s_waitcnt lgkmcnt(6)
	v_mfma_f32_32x32x16_bf16 v[64:79], v[6:9], v[176:179], v[64:79]
	ds_read_b64_tr_b16 v[196:197], v200 offset:0x1200
	ds_read_b64_tr_b16 v[198:199], v200 offset:0x1a00
	s_waitcnt lgkmcnt(6)
	v_mfma_f32_32x32x16_bf16 v[64:79], v[10:13], v[220:223], v[64:79]
	ds_read_b64_tr_b16 v[220:221], v200 offset:0x2200
	ds_read_b64_tr_b16 v[222:223], v200 offset:0x2a00
	s_waitcnt lgkmcnt(6)
	v_mfma_f32_32x32x16_bf16 v[64:79], v[184:187], v[244:247], v[64:79]
	ds_read_b64_tr_b16 v[244:245], v200 offset:0x3200
	ds_read_b64_tr_b16 v[246:247], v200 offset:0x3a00
	s_waitcnt lgkmcnt(6)
	v_mfma_f32_32x32x16_bf16 v[48:63], v[2:5], v[192:195], v[48:63]
	ds_read_b64_tr_b16 v[192:193], v200 offset:0x400
	ds_read_b64_tr_b16 v[194:195], v200 offset:0xc00
	s_waitcnt lgkmcnt(6)
	v_mfma_f32_32x32x16_bf16 v[48:63], v[6:9], v[196:199], v[48:63]
	ds_read_b64_tr_b16 v[196:197], v200 offset:0x1400
	ds_read_b64_tr_b16 v[198:199], v200 offset:0x1c00
	s_waitcnt lgkmcnt(6)
	v_mfma_f32_32x32x16_bf16 v[48:63], v[10:13], v[220:223], v[48:63]
	ds_read_b64_tr_b16 v[220:221], v200 offset:0x2400
	ds_read_b64_tr_b16 v[222:223], v200 offset:0x2c00
	s_waitcnt lgkmcnt(6)
	v_mfma_f32_32x32x16_bf16 v[48:63], v[184:187], v[244:247], v[48:63]
	ds_read_b64_tr_b16 v[244:245], v200 offset:0x3400
	ds_read_b64_tr_b16 v[246:247], v200 offset:0x3c00
	s_waitcnt lgkmcnt(6)
	v_mfma_f32_32x32x16_bf16 v[32:47], v[2:5], v[192:195], v[32:47]
	ds_read_b64_tr_b16 v[192:193], v200 offset:0x600
	ds_read_b64_tr_b16 v[194:195], v200 offset:0xe00
	s_waitcnt lgkmcnt(6)
	v_mfma_f32_32x32x16_bf16 v[32:47], v[6:9], v[196:199], v[32:47]
	ds_read_b64_tr_b16 v[196:197], v200 offset:0x1600
	ds_read_b64_tr_b16 v[198:199], v200 offset:0x1e00
	s_waitcnt lgkmcnt(6)
	v_mfma_f32_32x32x16_bf16 v[32:47], v[10:13], v[220:223], v[32:47]
	ds_read_b64_tr_b16 v[220:221], v200 offset:0x2600
	ds_read_b64_tr_b16 v[222:223], v200 offset:0x2e00
	s_waitcnt lgkmcnt(6)
	v_mfma_f32_32x32x16_bf16 v[32:47], v[184:187], v[244:247], v[32:47]
	ds_read_b64_tr_b16 v[244:245], v200 offset:0x3600
	ds_read_b64_tr_b16 v[246:247], v200 offset:0x3e00
	s_waitcnt lgkmcnt(6)
	v_mfma_f32_32x32x16_bf16 v[16:31], v[2:5], v[192:195], v[16:31]
	s_waitcnt lgkmcnt(4)
	v_mfma_f32_32x32x16_bf16 v[16:31], v[6:9], v[196:199], v[16:31]
	s_waitcnt lgkmcnt(2)
	v_mfma_f32_32x32x16_bf16 v[16:31], v[10:13], v[220:223], v[16:31]
	s_waitcnt lgkmcnt(0)
	v_mfma_f32_32x32x16_bf16 v[16:31], v[184:187], v[244:247], v[16:31]
	s_setprio 0
	s_waitcnt lgkmcnt(0)
	s_barrier
	s_andn2_b64 vcc, exec, s[2:3]
	s_cbranch_vccnz .LBB0_631
	s_and_b32 s2, s35, 3
	s_lshl_b32 s3, s2, 14
	s_add_i32 s3, s3, 0
	v_add_u32_e32 v2, s3, v233
	v_add_u32_e32 v3, s3, v234
	v_lshl_add_u32 v4, s2, 13, v235
	s_waitcnt vmcnt(2)
	ds_write_b128 v2, v[160:163]
	s_waitcnt vmcnt(1)
	ds_write_b128 v3, v[164:167]
	s_waitcnt vmcnt(0)
	ds_write_b128 v4, v[168:171]
